# speedup vs baseline: 1.0080x; 1.0073x over previous
.LBB0_562:
	v_ashrrev_i32_e32 v69, 31, v68
	v_mov_b64_e32 v[0:1], s[96:97]
	v_add_u32_e32 v98, 0x9000, v68
	v_mad_i64_i32 v[92:93], s[0:1], v68, s43, v[0:1]
	v_mov_b32_e32 v89, v96
	v_lshlrev_b64 v[0:1], 10, v[68:69]
	v_ashrrev_i32_e32 v99, 31, v98
	v_lshl_add_u64 v[90:91], v[92:93], 0, v[88:89]
	v_lshl_add_u64 v[6:7], v[70:71], 0, v[0:1]
	v_lshlrev_b64 v[10:11], 10, v[98:99]
	global_load_dwordx4 v[2:5], v[90:91], off offset:3072
	v_lshl_add_u64 v[10:11], v[70:71], 0, v[10:11]
	global_load_dwordx4 v[6:9], v[6:7], off
	v_lshl_add_u64 v[0:1], v[72:73], 0, v[0:1]
	global_load_dwordx4 v[100:103], v[10:11], off
	v_cmp_lt_i32_e32 vcc, s42, v68
	v_mov_b32_e32 v111, 0
	s_waitcnt vmcnt(2)
	v_lshlrev_b32_e32 v10, 16, v2
	v_and_b32_e32 v11, 0xffff0000, v2
	s_waitcnt vmcnt(1)
	v_lshlrev_b32_e32 v94, 16, v6
	v_and_b32_e32 v95, 0xffff0000, v6
	v_lshlrev_b32_e32 v2, 16, v3
	v_and_b32_e32 v3, 0xffff0000, v3
	v_lshlrev_b32_e32 v6, 16, v7
	v_and_b32_e32 v7, 0xffff0000, v7
	s_waitcnt vmcnt(0)
	v_lshlrev_b32_e32 v108, 16, v100
	v_and_b32_e32 v109, 0xffff0000, v100
	v_pk_fma_f32 v[10:11], v[12:13], v[10:11], v[94:95]
	v_lshlrev_b32_e32 v94, 16, v101
	v_and_b32_e32 v95, 0xffff0000, v101
	v_pk_fma_f32 v[2:3], v[26:27], v[2:3], v[6:7]
	v_pk_add_f32 v[10:11], v[10:11], v[108:109]
	v_lshlrev_b32_e32 v104, 16, v4
	v_and_b32_e32 v105, 0xffff0000, v4
	v_lshlrev_b32_e32 v106, 16, v8
	v_and_b32_e32 v107, 0xffff0000, v8
	v_lshlrev_b32_e32 v6, 16, v102
	v_and_b32_e32 v7, 0xffff0000, v102
	v_pk_add_f32 v[2:3], v[2:3], v[94:95]
	v_mul_f32_e32 v89, 0x3d372713, v10
	v_mul_f32_e32 v102, 0x3d372713, v11
	v_pk_fma_f32 v[100:101], v[40:41], v[104:105], v[106:107]
	v_mul_f32_e32 v106, 0x3d372713, v2
	v_mul_f32_e32 v107, 0x3d372713, v3
	v_mul_f32_e32 v89, v10, v89
	v_mul_f32_e32 v102, v11, v102
	v_pk_mul_f32 v[94:95], v[10:11], 0.5 op_sel_hi:[1,0]
	v_mul_f32_e32 v106, v2, v106
	v_mul_f32_e32 v107, v3, v107
	v_fma_f32 v10, v10, v89, v10
	v_fmac_f32_e32 v11, v11, v102
	v_pk_add_f32 v[6:7], v[100:101], v[6:7]
	v_pk_mul_f32 v[100:101], v[2:3], 0.5 op_sel_hi:[1,0]
	v_fma_f32 v2, v2, v106, v2
	v_fmac_f32_e32 v3, v3, v107
	v_mul_f32_e32 v10, 0x3f4c422a, v10
	v_mul_f32_e32 v11, 0x3f4c422a, v11
	v_mul_f32_e32 v109, 0x3d372713, v7
	v_mul_f32_e32 v2, 0x3f4c422a, v2
	v_mul_f32_e32 v3, 0x3f4c422a, v3
	v_add_f32_e32 v10, v10, v10
	v_add_f32_e32 v11, v11, v11
	v_mul_f32_e32 v109, v7, v109
	v_add_f32_e32 v2, v2, v2
	v_add_f32_e32 v3, v3, v3
	v_mul_f32_e32 v10, 0x3fb8aa3b, v10
	v_mul_f32_e32 v11, 0x3fb8aa3b, v11
	v_pk_mul_f32 v[104:105], v[6:7], 0.5 op_sel_hi:[1,0]
	v_fmac_f32_e32 v7, v7, v109
	v_mul_f32_e32 v2, 0x3fb8aa3b, v2
	v_mul_f32_e32 v3, 0x3fb8aa3b, v3
	v_exp_f32_e32 v10, v10
	v_exp_f32_e32 v11, v11
	v_mul_f32_e32 v7, 0x3f4c422a, v7
	v_exp_f32_e32 v2, v2
	v_exp_f32_e32 v3, v3
	v_add_f32_e32 v7, v7, v7
	v_mul_f32_e32 v7, 0x3fb8aa3b, v7
	v_exp_f32_e32 v89, v7
	v_add_f32_e32 v7, 1.0, v10
	v_add_f32_e32 v10, 1.0, v11
	v_add_f32_e32 v11, 1.0, v2
	v_add_f32_e32 v102, 1.0, v3
	v_rcp_f32_e32 v2, v7
	v_rcp_f32_e32 v3, v10
	v_mul_f32_e32 v108, 0x3d372713, v6
	v_lshlrev_b32_e32 v4, 16, v5
	v_and_b32_e32 v5, 0xffff0000, v5
	v_pk_fma_f32 v[2:3], v[2:3], 2.0, 1.0 op_sel_hi:[1,0,0] neg_lo:[1,0,0] neg_hi:[1,0,0]
	v_lshlrev_b32_e32 v8, 16, v9
	v_mul_f32_e32 v108, v6, v108
	v_pk_add_f32 v[2:3], v[2:3], 1.0 op_sel_hi:[1,0]
	v_and_b32_e32 v9, 0xffff0000, v9
	v_fma_f32 v6, v6, v108, v6
	v_pk_mul_f32 v[2:3], v[94:95], v[2:3]
	v_lshlrev_b32_e32 v94, 16, v103
	v_and_b32_e32 v95, 0xffff0000, v103
	v_pk_fma_f32 v[4:5], v[54:55], v[4:5], v[8:9]
	v_mul_f32_e32 v6, 0x3f4c422a, v6
	v_pk_add_f32 v[4:5], v[4:5], v[94:95]
	v_add_f32_e32 v6, v6, v6
	v_mul_f32_e32 v8, 0x3d372713, v4
	v_mul_f32_e32 v6, 0x3fb8aa3b, v6
	v_mul_f32_e32 v8, v4, v8
	v_exp_f32_e32 v6, v6
	v_fma_f32 v8, v4, v8, v4
	v_mul_f32_e32 v8, 0x3f4c422a, v8
	v_add_f32_e32 v8, v8, v8
	v_mul_f32_e32 v8, 0x3fb8aa3b, v8
	v_add_f32_e32 v106, 1.0, v6
	v_rcp_f32_e32 v6, v11
	v_add_f32_e32 v11, 1.0, v89
	v_exp_f32_e32 v89, v8
	v_pk_mul_f32 v[8:9], v[4:5], 0.5 op_sel_hi:[1,0]
	v_mul_f32_e32 v4, 0x3d372713, v5
	v_mul_f32_e32 v4, v5, v4
	v_fmac_f32_e32 v5, v5, v4
	v_mul_f32_e32 v4, 0x3f4c422a, v5
	v_add_f32_e32 v4, v4, v4
	v_mul_f32_e32 v4, 0x3fb8aa3b, v4
	v_exp_f32_e32 v5, v4
	v_add_f32_e32 v4, 1.0, v89
	v_rcp_f32_e32 v7, v102
	v_rcp_f32_e32 v10, v106
	v_add_f32_e32 v5, 1.0, v5
	v_rcp_f32_e32 v11, v11
	v_rcp_f32_e32 v4, v4
	v_rcp_f32_e32 v5, v5
	v_pk_fma_f32 v[6:7], v[6:7], 2.0, 1.0 op_sel_hi:[1,0,0] neg_lo:[1,0,0] neg_hi:[1,0,0]
	v_pk_fma_f32 v[10:11], v[10:11], 2.0, 1.0 op_sel_hi:[1,0,0] neg_lo:[1,0,0] neg_hi:[1,0,0]
	v_pk_add_f32 v[6:7], v[6:7], 1.0 op_sel_hi:[1,0]
	v_pk_fma_f32 v[4:5], v[4:5], 2.0, 1.0 op_sel_hi:[1,0,0] neg_lo:[1,0,0] neg_hi:[1,0,0]
	v_pk_add_f32 v[10:11], v[10:11], 1.0 op_sel_hi:[1,0]
	v_pk_add_f32 v[4:5], v[4:5], 1.0 op_sel_hi:[1,0]
	v_pk_mul_f32 v[6:7], v[100:101], v[6:7]
	v_pk_mul_f32 v[10:11], v[104:105], v[10:11]
	v_pk_mul_f32 v[8:9], v[8:9], v[4:5]
	v_cvt_pk_bf16_f32 v2, v2, v3
	v_cvt_pk_bf16_f32 v3, v6, v7
	v_cvt_pk_bf16_f32 v4, v10, v11
	v_cvt_pk_bf16_f32 v5, v8, v9
	global_store_dwordx4 v[0:1], v[2:5], off
	v_mov_b32_e32 v89, 0
	s_nop 0
	v_lshlrev_b32_e32 v4, 1, v74
	v_mov_b32_e32 v5, v96
	v_lshl_add_u64 v[0:1], v[92:93], 0, v[4:5]
	global_load_dwordx4 v[0:3], v[0:1], off
	v_cndmask_b32_e32 v5, v222, v223, vcc
	v_and_b32_e32 v6, v5, v68
	v_cmp_ne_u32_e32 vcc, 0, v6
	v_mov_b32_e32 v164, 0
	v_mov_b32_e32 v165, 0
	v_mov_b32_e32 v166, 0
	v_mov_b32_e32 v167, 0
	s_and_saveexec_b64 s[0:1], vcc
	global_load_dwordx4 v[164:167], v[90:91], off offset:-3840
	s_mov_b64 exec, s[0:1]
	s_or_b64 exec, exec, s[0:1]
	s_or_b64 exec, exec, s[0:1]
	v_mov_b32_e32 v123, 0
	v_mov_b32_e32 v122, 0
	s_or_b64 exec, exec, s[0:1]
	s_or_b64 exec, exec, s[0:1]
	v_mov_b32_e32 v125, 0
	v_mov_b32_e32 v124, 0
	s_or_b64 exec, exec, s[0:1]
	s_or_b64 exec, exec, s[0:1]
	v_mov_b32_e32 v134, 0
	v_mov_b32_e32 v133, 0
	s_or_b64 exec, exec, s[0:1]
	s_or_b64 exec, exec, s[0:1]
	s_mov_b64 s[0:1], 0x1f00
	v_cmp_ne_u32_e64 s[6:7], v6, v5
	v_lshl_add_u64 v[94:95], v[92:93], 0, s[0:1]
	v_mov_b32_e32 v5, v96
	v_lshl_add_u64 v[4:5], v[94:95], 0, v[4:5]
	v_mov_b32_e32 v136, 0
	v_mov_b32_e32 v135, 0
	v_mov_b32_e32 v168, 0
	v_mov_b32_e32 v169, 0
	v_mov_b32_e32 v170, 0
	v_mov_b32_e32 v171, 0
	s_and_saveexec_b64 s[0:1], s[6:7]
	global_load_dwordx4 v[168:171], v[4:5], off
	s_mov_b64 exec, s[0:1]
	s_or_b64 exec, exec, s[0:1]
	s_or_b64 exec, exec, s[0:1]
	v_mov_b32_e32 v138, 0
	v_mov_b32_e32 v137, 0
	s_or_b64 exec, exec, s[0:1]
	s_or_b64 exec, exec, s[0:1]
	v_mov_b32_e32 v140, 0
	v_mov_b32_e32 v139, 0
	s_or_b64 exec, exec, s[0:1]
	s_or_b64 exec, exec, s[0:1]
	v_mov_b32_e32 v141, 0
	v_mov_b32_e32 v142, 0
	s_or_b64 exec, exec, s[0:1]
	s_or_b64 exec, exec, s[0:1]
	v_lshlrev_b32_e32 v8, 1, v84
	v_mov_b32_e32 v9, v96
	v_lshl_add_u64 v[4:5], v[92:93], 0, v[8:9]
	global_load_dwordx4 v[4:7], v[4:5], off
	v_mov_b32_e32 v115, 0
	v_mov_b32_e32 v114, 0
	v_mov_b32_e32 v172, 0
	v_mov_b32_e32 v173, 0
	v_mov_b32_e32 v174, 0
	v_mov_b32_e32 v175, 0
	s_and_saveexec_b64 s[0:1], vcc
	global_load_dwordx4 v[172:175], v[90:91], off offset:-2816
	s_mov_b64 exec, s[0:1]
	s_or_b64 exec, exec, s[0:1]
	s_or_b64 exec, exec, s[0:1]
	v_mov_b32_e32 v117, 0
	v_mov_b32_e32 v116, 0
	s_or_b64 exec, exec, s[0:1]
	s_or_b64 exec, exec, s[0:1]
	v_mov_b32_e32 v119, 0
	v_mov_b32_e32 v118, 0
	s_or_b64 exec, exec, s[0:1]
	s_or_b64 exec, exec, s[0:1]
	v_mov_b32_e32 v121, 0
	v_mov_b32_e32 v120, 0
	s_or_b64 exec, exec, s[0:1]
	s_or_b64 exec, exec, s[0:1]
	v_mov_b32_e32 v9, v96
	v_lshl_add_u64 v[8:9], v[94:95], 0, v[8:9]
	v_mov_b32_e32 v144, 0
	v_mov_b32_e32 v143, 0
	v_mov_b32_e32 v176, 0
	v_mov_b32_e32 v177, 0
	v_mov_b32_e32 v178, 0
	v_mov_b32_e32 v179, 0
	s_and_saveexec_b64 s[0:1], s[6:7]
	global_load_dwordx4 v[176:179], v[8:9], off
	s_mov_b64 exec, s[0:1]
	s_or_b64 exec, exec, s[0:1]
	s_or_b64 exec, exec, s[0:1]
	v_mov_b32_e32 v146, 0
	v_mov_b32_e32 v145, 0
	s_or_b64 exec, exec, s[0:1]
	s_or_b64 exec, exec, s[0:1]
	v_mov_b32_e32 v149, 0
	v_mov_b32_e32 v148, 0
	s_or_b64 exec, exec, s[0:1]
	s_or_b64 exec, exec, s[0:1]
	v_mov_b32_e32 v147, 0
	v_mov_b32_e32 v150, 0
	s_or_b64 exec, exec, s[0:1]
	s_or_b64 exec, exec, s[0:1]
	v_lshlrev_b32_e32 v100, 1, v86
	v_mov_b32_e32 v101, v96
	v_lshl_add_u64 v[8:9], v[92:93], 0, v[100:101]
	global_load_dwordx4 v[8:11], v[8:9], off
	v_mov_b32_e32 v152, 0
	v_mov_b32_e32 v151, 0
	v_mov_b32_e32 v180, 0
	v_mov_b32_e32 v181, 0
	v_mov_b32_e32 v182, 0
	v_mov_b32_e32 v183, 0
	s_and_saveexec_b64 s[0:1], vcc
	global_load_dwordx4 v[180:183], v[90:91], off offset:-1792
	s_mov_b64 exec, s[0:1]
	s_or_b64 exec, exec, s[0:1]
	s_or_b64 exec, exec, s[0:1]
	v_mov_b32_e32 v105, 0
	v_mov_b32_e32 v104, 0
	s_or_b64 exec, exec, s[0:1]
	s_or_b64 exec, exec, s[0:1]
	v_mov_b32_e32 v109, 0
	v_mov_b32_e32 v108, 0
	s_or_b64 exec, exec, s[0:1]
	s_or_b64 exec, exec, s[0:1]
	v_mov_b32_e32 v113, 0
	v_mov_b32_e32 v112, 0
	s_or_b64 exec, exec, s[0:1]
	s_or_b64 exec, exec, s[0:1]
	v_mov_b32_e32 v101, v96
	v_lshl_add_u64 v[100:101], v[94:95], 0, v[100:101]
	v_mov_b32_e32 v155, 0
	v_mov_b32_e32 v154, 0
	v_mov_b32_e32 v184, 0
	v_mov_b32_e32 v185, 0
	v_mov_b32_e32 v186, 0
	v_mov_b32_e32 v187, 0
	s_and_saveexec_b64 s[0:1], s[6:7]
	global_load_dwordx4 v[184:187], v[100:101], off
	s_mov_b64 exec, s[0:1]
	s_or_b64 exec, exec, s[0:1]
	s_or_b64 exec, exec, s[0:1]
	v_mov_b32_e32 v103, 0
	v_mov_b32_e32 v102, 0
	s_or_b64 exec, exec, s[0:1]
	s_or_b64 exec, exec, s[0:1]
	v_mov_b32_e32 v107, 0
	v_mov_b32_e32 v106, 0
	s_or_b64 exec, exec, s[0:1]
	s_or_b64 exec, exec, s[0:1]
	v_mov_b32_e32 v153, 0
	v_mov_b32_e32 v110, 0
	s_or_b64 exec, exec, s[0:1]
	s_or_b64 exec, exec, s[0:1]
	v_lshlrev_b64 v[126:127], 9, v[98:99]
	s_waitcnt vmcnt(0)
	v_mov_b32_e32 v111, v164
	v_mov_b32_e32 v89, v164
	v_mov_b32_e32 v122, v165
	v_mov_b32_e32 v123, v165
	v_mov_b32_e32 v124, v166
	v_mov_b32_e32 v125, v166
	v_mov_b32_e32 v133, v167
	v_mov_b32_e32 v134, v167
	v_mov_b32_e32 v135, v168
	v_mov_b32_e32 v136, v168
	v_mov_b32_e32 v137, v169
	v_mov_b32_e32 v138, v169
	v_mov_b32_e32 v139, v170
	v_mov_b32_e32 v140, v170
	v_mov_b32_e32 v142, v171
	v_mov_b32_e32 v141, v171
	v_mov_b32_e32 v114, v172
	v_mov_b32_e32 v115, v172
	v_mov_b32_e32 v116, v173
	v_mov_b32_e32 v117, v173
	v_mov_b32_e32 v118, v174
	v_mov_b32_e32 v119, v174
	v_mov_b32_e32 v120, v175
	v_mov_b32_e32 v121, v175
	v_mov_b32_e32 v143, v176
	v_mov_b32_e32 v144, v176
	v_mov_b32_e32 v145, v177
	v_mov_b32_e32 v146, v177
	v_mov_b32_e32 v148, v178
	v_mov_b32_e32 v149, v178
	v_mov_b32_e32 v150, v179
	v_mov_b32_e32 v147, v179
	v_mov_b32_e32 v151, v180
	v_mov_b32_e32 v152, v180
	v_mov_b32_e32 v104, v181
	v_mov_b32_e32 v105, v181
	v_mov_b32_e32 v108, v182
	v_mov_b32_e32 v109, v182
	v_mov_b32_e32 v112, v183
	v_mov_b32_e32 v113, v183
	v_mov_b32_e32 v154, v184
	v_mov_b32_e32 v155, v184
	v_mov_b32_e32 v102, v185
	v_mov_b32_e32 v103, v185
	v_mov_b32_e32 v106, v186
	v_mov_b32_e32 v107, v186
	v_mov_b32_e32 v110, v187
	v_mov_b32_e32 v153, v187
	v_lshlrev_b32_e32 v98, 16, v154
	v_lshlrev_b32_e32 v154, 16, v145
	v_and_b32_e32 v145, 0xffff0000, v144
	v_lshlrev_b32_e32 v144, 16, v143
	v_and_b32_e32 v115, 0xffff0000, v115
	v_lshlrev_b32_e32 v114, 16, v114
	v_and_b32_e32 v159, 0xffff0000, v119
	v_lshlrev_b32_e32 v158, 16, v118
	v_lshlrev_b32_e32 v118, 16, v4
	v_and_b32_e32 v119, 0xffff0000, v4
	v_pk_add_f32 v[114:115], v[114:115], v[144:145]
	v_and_b32_e32 v99, 0xffff0000, v155
	v_and_b32_e32 v155, 0xffff0000, v146
	v_and_b32_e32 v117, 0xffff0000, v117
	v_lshlrev_b32_e32 v116, 16, v116
	v_pk_fma_f32 v[114:115], v[114:115], 0.5, v[118:119] op_sel_hi:[1,0,1] neg_lo:[0,0,1] neg_hi:[0,0,1]
	v_and_b32_e32 v157, 0xffff0000, v121
	v_lshlrev_b32_e32 v156, 16, v120
	v_lshlrev_b32_e32 v4, 16, v5
	v_and_b32_e32 v5, 0xffff0000, v5
	v_pk_fma_f32 v[120:121], v[22:23], v[114:115], v[118:119]
	v_pk_add_f32 v[114:115], v[116:117], v[154:155]
	v_and_b32_e32 v149, 0xffff0000, v149
	v_lshlrev_b32_e32 v148, 16, v148
	v_pk_fma_f32 v[114:115], v[114:115], 0.5, v[4:5] op_sel_hi:[1,0,1] neg_lo:[0,0,1] neg_hi:[0,0,1]
	v_lshlrev_b32_e32 v160, 16, v6
	v_and_b32_e32 v161, 0xffff0000, v6
	v_pk_fma_f32 v[118:119], v[36:37], v[114:115], v[4:5]
	v_pk_add_f32 v[4:5], v[158:159], v[148:149]
	v_lshlrev_b32_e32 v100, 16, v151
	v_lshlrev_b32_e32 v150, 16, v150
	v_and_b32_e32 v151, 0xffff0000, v147
	v_pk_fma_f32 v[4:5], v[4:5], 0.5, v[160:161] op_sel_hi:[1,0,1] neg_lo:[0,0,1] neg_hi:[0,0,1]
	v_lshlrev_b32_e32 v144, 16, v139
	v_and_b32_e32 v139, 0xffff0000, v138
	v_lshlrev_b32_e32 v138, 16, v137
	v_and_b32_e32 v137, 0xffff0000, v136
	v_lshlrev_b32_e32 v136, 16, v135
	v_and_b32_e32 v147, 0xffff0000, v125
	v_lshlrev_b32_e32 v146, 16, v124
	v_and_b32_e32 v125, 0xffff0000, v89
	v_lshlrev_b32_e32 v124, 16, v111
	v_pk_fma_f32 v[116:117], v[50:51], v[4:5], v[160:161]
	v_pk_add_f32 v[4:5], v[156:157], v[150:151]
	v_lshlrev_b32_e32 v148, 16, v0
	v_and_b32_e32 v149, 0xffff0000, v0
	v_lshlrev_b32_e32 v150, 16, v2
	v_and_b32_e32 v151, 0xffff0000, v2
	v_lshlrev_b32_e32 v154, 16, v3
	v_and_b32_e32 v155, 0xffff0000, v3
	v_pk_add_f32 v[2:3], v[124:125], v[136:137]
	v_and_b32_e32 v123, 0xffff0000, v123
	v_lshlrev_b32_e32 v122, 16, v122
	v_pk_fma_f32 v[2:3], v[2:3], 0.5, v[148:149] op_sel_hi:[1,0,1] neg_lo:[0,0,1] neg_hi:[0,0,1]
	v_lshlrev_b32_e32 v0, 16, v1
	v_and_b32_e32 v1, 0xffff0000, v1
	v_pk_fma_f32 v[124:125], v[20:21], v[2:3], v[148:149]
	v_pk_add_f32 v[2:3], v[122:123], v[138:139]
	v_and_b32_e32 v145, 0xffff0000, v140
	v_pk_fma_f32 v[2:3], v[2:3], 0.5, v[0:1] op_sel_hi:[1,0,1] neg_lo:[0,0,1] neg_hi:[0,0,1]
	v_lshlrev_b64 v[128:129], 9, v[68:69]
	v_pk_fma_f32 v[122:123], v[34:35], v[2:3], v[0:1]
	v_pk_add_f32 v[0:1], v[146:147], v[144:145]
	v_lshlrev_b32_e32 v142, 16, v142
	v_and_b32_e32 v135, 0xffff0000, v134
	v_lshlrev_b32_e32 v134, 16, v133
	v_and_b32_e32 v143, 0xffff0000, v141
	v_pk_fma_f32 v[0:1], v[0:1], 0.5, v[150:151] op_sel_hi:[1,0,1] neg_lo:[0,0,1] neg_hi:[0,0,1]
	v_lshlrev_b64 v[128:129], 1, v[128:129]
	v_pk_fma_f32 v[2:3], v[48:49], v[0:1], v[150:151]
	v_pk_add_f32 v[0:1], v[134:135], v[142:143]
	v_lshl_add_u64 v[134:135], v[76:77], 0, v[128:129]
	v_lshl_add_u64 v[126:127], v[126:127], 1, v[76:77]
	global_load_dwordx4 v[134:137], v[134:135], off
	v_pk_mul_f32 v[120:121], v[124:125], v[120:121]
	global_load_dwordx4 v[138:141], v[126:127], off
	v_pk_mul_f32 v[120:121], v[18:19], v[120:121]
	v_pk_mul_f32 v[118:119], v[122:123], v[118:119]
	v_add_f32_e32 v89, 0, v120
	v_lshlrev_b32_e32 v6, 16, v7
	v_and_b32_e32 v7, 0xffff0000, v7
	v_add_f32_e32 v89, v89, v121
	v_pk_mul_f32 v[118:119], v[32:33], v[118:119]
	v_and_b32_e32 v101, 0xffff0000, v152
	v_pk_fma_f32 v[4:5], v[4:5], 0.5, v[6:7] op_sel_hi:[1,0,1] neg_lo:[0,0,1] neg_hi:[0,0,1]
	v_pk_fma_f32 v[0:1], v[0:1], 0.5, v[154:155] op_sel_hi:[1,0,1] neg_lo:[0,0,1] neg_hi:[0,0,1]
	v_add_f32_e32 v89, v89, v118
	v_pk_mul_f32 v[2:3], v[2:3], v[116:117]
	v_pk_fma_f32 v[114:115], v[64:65], v[4:5], v[6:7]
	v_lshlrev_b32_e32 v4, 16, v8
	v_and_b32_e32 v5, 0xffff0000, v8
	v_pk_fma_f32 v[0:1], v[62:63], v[0:1], v[154:155]
	v_add_f32_e32 v89, v89, v119
	v_pk_mul_f32 v[2:3], v[46:47], v[2:3]
	v_pk_add_f32 v[98:99], v[100:101], v[98:99]
	v_and_b32_e32 v103, 0xffff0000, v103
	v_lshlrev_b32_e32 v102, 16, v102
	v_and_b32_e32 v105, 0xffff0000, v105
	v_lshlrev_b32_e32 v104, 16, v104
	v_add_f32_e32 v2, v89, v2
	v_pk_mul_f32 v[0:1], v[0:1], v[114:115]
	v_pk_fma_f32 v[98:99], v[98:99], 0.5, v[4:5] op_sel_hi:[1,0,1] neg_lo:[0,0,1] neg_hi:[0,0,1]
	v_lshlrev_b32_e32 v6, 16, v9
	v_and_b32_e32 v7, 0xffff0000, v9
	v_add_f32_e32 v2, v2, v3
	v_pk_mul_f32 v[0:1], v[60:61], v[0:1]
	v_pk_add_f32 v[102:103], v[104:105], v[102:103]
	v_pk_fma_f32 v[4:5], v[24:25], v[98:99], v[4:5]
	v_and_b32_e32 v107, 0xffff0000, v107
	v_lshlrev_b32_e32 v106, 16, v106
	v_and_b32_e32 v109, 0xffff0000, v109
	v_lshlrev_b32_e32 v108, 16, v108
	v_add_f32_e32 v0, v2, v0
	v_pk_fma_f32 v[102:103], v[102:103], 0.5, v[6:7] op_sel_hi:[1,0,1] neg_lo:[0,0,1] neg_hi:[0,0,1]
	v_lshlrev_b32_e32 v8, 16, v10
	v_and_b32_e32 v9, 0xffff0000, v10
	v_add_f32_e32 v0, v0, v1
	v_pk_add_f32 v[106:107], v[108:109], v[106:107]
	v_pk_fma_f32 v[6:7], v[38:39], v[102:103], v[6:7]
	v_lshlrev_b32_e32 v110, 16, v110
	v_and_b32_e32 v113, 0xffff0000, v113
	v_lshlrev_b32_e32 v112, 16, v112
	v_and_b32_e32 v111, 0xffff0000, v153
	v_pk_fma_f32 v[106:107], v[106:107], 0.5, v[8:9] op_sel_hi:[1,0,1] neg_lo:[0,0,1] neg_hi:[0,0,1]
	v_lshlrev_b32_e32 v10, 16, v11
	v_and_b32_e32 v11, 0xffff0000, v11
	v_pk_add_f32 v[2:3], v[112:113], v[110:111]
	v_pk_fma_f32 v[8:9], v[52:53], v[106:107], v[8:9]
	v_pk_fma_f32 v[2:3], v[2:3], 0.5, v[10:11] op_sel_hi:[1,0,1] neg_lo:[0,0,1] neg_hi:[0,0,1]
	v_add_f32_dpp v0, v0, v0 quad_perm:[1,0,3,2] row_mask:0xf bank_mask:0xf bound_ctrl:1
	v_pk_fma_f32 v[2:3], v[66:67], v[2:3], v[10:11]
	s_waitcnt vmcnt(1)
	v_lshlrev_b32_e32 v98, 16, v134
	v_and_b32_e32 v99, 0xffff0000, v134
	s_waitcnt vmcnt(0)
	v_lshlrev_b32_e32 v100, 16, v138
	v_and_b32_e32 v101, 0xffff0000, v138
	v_pk_add_f32 v[98:99], v[98:99], v[100:101]
	v_lshlrev_b32_e32 v102, 16, v135
	v_and_b32_e32 v103, 0xffff0000, v135
	v_lshlrev_b32_e32 v104, 16, v139
	v_and_b32_e32 v105, 0xffff0000, v139
	v_add_f32_e32 v1, 0, v98
	v_pk_add_f32 v[102:103], v[102:103], v[104:105]
	v_add_f32_e32 v1, v99, v1
	v_lshlrev_b32_e32 v106, 16, v136
	v_and_b32_e32 v107, 0xffff0000, v136
	v_lshlrev_b32_e32 v108, 16, v140
	v_and_b32_e32 v109, 0xffff0000, v140
	v_add_f32_e32 v1, v102, v1
	v_pk_add_f32 v[106:107], v[106:107], v[108:109]
	v_add_f32_e32 v1, v103, v1
	v_lshlrev_b32_e32 v10, 16, v137
	v_and_b32_e32 v11, 0xffff0000, v137
	v_lshlrev_b32_e32 v110, 16, v141
	v_and_b32_e32 v111, 0xffff0000, v141
	v_add_f32_e32 v1, v106, v1
	v_pk_add_f32 v[10:11], v[10:11], v[110:111]
	v_add_f32_e32 v1, v107, v1
	v_add_f32_e32 v1, v10, v1
	v_add_f32_e32 v1, v11, v1
	v_add_f32_dpp v0, v0, v0 quad_perm:[2,3,0,1] row_mask:0xf bank_mask:0xf bound_ctrl:1
	s_nop 0
	v_add_f32_dpp v1, v1, v1 quad_perm:[1,0,3,2] row_mask:0xf bank_mask:0xf bound_ctrl:1
	v_add_f32_dpp v0, v0, v0 row_half_mirror row_mask:0xf bank_mask:0xf bound_ctrl:1
	s_nop 0
	v_add_f32_dpp v1, v1, v1 quad_perm:[2,3,0,1] row_mask:0xf bank_mask:0xf bound_ctrl:1
	s_nop 1
	v_add_f32_dpp v1, v1, v1 row_half_mirror row_mask:0xf bank_mask:0xf bound_ctrl:1
	v_mul_f32_e32 v100, 0x3c800000, v1
	v_pk_add_f32 v[98:99], v[98:99], v[100:101] op_sel_hi:[1,0] neg_lo:[0,1] neg_hi:[0,1]
	v_pk_add_f32 v[102:103], v[102:103], v[100:101] op_sel_hi:[1,0] neg_lo:[0,1] neg_hi:[0,1]
	v_pk_mul_f32 v[104:105], v[98:99], v[98:99]
	v_pk_mul_f32 v[108:109], v[102:103], v[102:103]
	v_add_f32_e32 v1, v104, v105
	v_pk_add_f32 v[106:107], v[106:107], v[100:101] op_sel_hi:[1,0] neg_lo:[0,1] neg_hi:[0,1]
	v_add_f32_e32 v1, v108, v1
	v_pk_mul_f32 v[110:111], v[106:107], v[106:107]
	v_add_f32_e32 v1, v109, v1
	v_pk_add_f32 v[10:11], v[10:11], v[100:101] op_sel_hi:[1,0] neg_lo:[0,1] neg_hi:[0,1]
	v_add_f32_e32 v1, v110, v1
	v_pk_mul_f32 v[100:101], v[10:11], v[10:11]
	v_add_f32_e32 v1, v111, v1
	v_add_f32_e32 v1, v100, v1
	v_add_f32_e32 v1, v101, v1
	s_nop 1
	v_add_f32_dpp v1, v1, v1 quad_perm:[1,0,3,2] row_mask:0xf bank_mask:0xf bound_ctrl:1
	s_nop 1
	v_add_f32_dpp v1, v1, v1 quad_perm:[2,3,0,1] row_mask:0xf bank_mask:0xf bound_ctrl:1
	s_nop 1
	v_add_f32_dpp v1, v1, v1 row_half_mirror row_mask:0xf bank_mask:0xf bound_ctrl:1
	v_fmamk_f32 v1, v1, 0x3c800000, v210
	v_cmp_gt_f32_e64 s[0:1], s33, v1
	v_mul_f32_e32 v89, 0x4b800000, v1
	s_nop 0
	v_cndmask_b32_e64 v1, v1, v89, s[0:1]
	v_rsq_f32_e32 v1, v1
	s_nop 0
	v_mul_f32_e32 v89, 0x45800000, v1
	v_cndmask_b32_e64 v100, v1, v89, s[0:1]
	v_pk_mul_f32 v[98:99], v[98:99], v[100:101] op_sel_hi:[1,0]
	v_pk_mul_f32 v[10:11], v[10:11], v[100:101] op_sel_hi:[1,0]
	v_pk_fma_f32 v[98:99], v[14:15], v[98:99], v[16:17]
	v_pk_fma_f32 v[10:11], v[56:57], v[10:11], v[58:59]
	v_pk_fma_f32 v[4:5], v[4:5], v[0:1], v[98:99] op_sel_hi:[1,0,1]
	v_pk_mul_f32 v[98:99], v[102:103], v[100:101] op_sel_hi:[1,0]
	v_pk_fma_f32 v[10:11], v[2:3], v[0:1], v[10:11] op_sel_hi:[1,0,1]
	v_pk_fma_f32 v[98:99], v[28:29], v[98:99], v[30:31]
	v_cvt_pk_bf16_f32 v3, v10, v11
	v_pk_fma_f32 v[6:7], v[6:7], v[0:1], v[98:99] op_sel_hi:[1,0,1]
	v_pk_mul_f32 v[98:99], v[106:107], v[100:101] op_sel_hi:[1,0]
	s_nop 0
	v_pk_fma_f32 v[98:99], v[42:43], v[98:99], v[44:45]
	s_nop 0
	v_pk_fma_f32 v[8:9], v[8:9], v[0:1], v[98:99] op_sel_hi:[1,0,1]
	v_cvt_pk_bf16_f32 v0, v4, v5
	v_cvt_pk_bf16_f32 v1, v6, v7
	v_cvt_pk_bf16_f32 v2, v8, v9
	v_lshl_add_u64 v[4:5], v[78:79], 0, v[128:129]
	global_store_dwordx4 v[4:5], v[0:3], off
	s_and_saveexec_b64 s[0:1], s[4:5]
	s_cbranch_execz .LBB0_561
	v_lshlrev_b32_e32 v8, 1, v80
	v_mov_b32_e32 v9, v96
	v_lshl_add_u64 v[0:1], v[92:93], 0, v[8:9]
	global_load_dwordx4 v[0:3], v[0:1], off
	v_mov_b32_e32 v164, 0
	v_mov_b32_e32 v165, 0
	v_mov_b32_e32 v166, 0
	v_mov_b32_e32 v167, 0
	v_mov_b32_e32 v168, 0
	v_mov_b32_e32 v169, 0
	v_mov_b32_e32 v170, 0
	v_mov_b32_e32 v171, 0
	s_and_saveexec_b64 s[12:13], vcc
	global_load_dwordx4 v[164:167], v[90:91], off offset:-256
	s_mov_b64 exec, s[12:13]
	v_mov_b32_e32 v9, v96
	v_lshl_add_u64 v[10:11], v[94:95], 0, v[8:9]
	s_and_saveexec_b64 s[12:13], s[6:7]
	global_load_dwordx4 v[168:171], v[10:11], off
	s_mov_b64 exec, s[12:13]
	s_waitcnt vmcnt(0)
	v_lshlrev_b32_e32 v98, 16, v164
	v_and_b32_e32 v93, 0xffff0000, v164
	v_lshlrev_b32_e32 v4, 16, v165
	v_mov_b32_e32 v5, v165
	v_lshlrev_b32_e32 v89, 16, v166
	v_mov_b32_e32 v99, v166
	v_lshlrev_b32_e32 v92, 16, v167
	v_mov_b32_e32 v100, v167
	v_lshlrev_b32_e32 v91, 16, v168
	v_and_b32_e32 v90, 0xffff0000, v168
	v_lshlrev_b32_e32 v6, 16, v169
	v_mov_b32_e32 v7, v169
	v_lshlrev_b32_e32 v9, 16, v170
	v_mov_b32_e32 v95, v170
	v_lshlrev_b32_e32 v8, 16, v171
	v_mov_b32_e32 v94, v171
	s_mov_b64 s[12:13], exec
	s_branch .LBB0_560
